# P3 delta items: conv weights staged once per WG in LDS, ds_read_b128 per item instead of 8 global loads
# baseline (speedup 1.0000x reference)
.LBB0_309:
	v_writelane_b32 v250, s97, 9
	v_writelane_b32 v250, s66, 6
	s_andn2_b64 vcc, exec, s[0:1]
	s_nop 0
	v_writelane_b32 v250, s67, 7
	v_writelane_b32 v250, s95, 8
	s_cbranch_vccnz .LBB0_460
	v_mbcnt_lo_u32_b32 v30, -1, 0
	v_mbcnt_hi_u32_b32 v36, -1, v30
	v_and_b32_e32 v31, 64, v36
	v_xor_b32_e32 v30, 1, v36
	v_add_u32_e32 v32, 64, v31
	v_cmp_lt_i32_e32 vcc, v30, v32
	s_movk_i32 s0, 0x27f
	s_add_i32 s3, 0, 0x4400
	v_cndmask_b32_e32 v37, v36, v30, vcc
	v_xor_b32_e32 v30, 2, v36
	v_cmp_lt_i32_e32 vcc, v30, v32
	s_cmp_lt_u32 s38, 64
	v_lshrrev_b32_e32 v56, 4, v1
	v_cndmask_b32_e32 v38, v36, v30, vcc
	v_xor_b32_e32 v30, 4, v36
	v_cmp_lt_i32_e32 vcc, v30, v32
	v_lshlrev_b32_e32 v58, 2, v56
	v_lshlrev_b32_e32 v86, 3, v0
	v_cndmask_b32_e32 v39, v36, v30, vcc
	v_xor_b32_e32 v30, 8, v36
	v_cmp_lt_i32_e32 vcc, v30, v32
	v_and_b32_e32 v57, 56, v86
	v_mov_b32_e32 v66, 0xffff
	v_cndmask_b32_e32 v40, v36, v30, vcc
	v_add_u32_e32 v30, -1, v36
	v_cmp_lt_i32_e32 vcc, v30, v31
	v_mov_b32_e32 v67, 0xffff0000
	v_or_b32_e32 v63, 2, v57
	v_cndmask_b32_e32 v41, v30, v36, vcc
	v_add_u32_e32 v30, -2, v36
	v_cmp_lt_i32_e32 vcc, v30, v31
	v_or_b32_e32 v65, 4, v57
	v_or_b32_e32 v80, 6, v57
	v_cndmask_b32_e32 v42, v30, v36, vcc
	v_add_u32_e32 v30, -4, v36
	v_cmp_lt_i32_e32 vcc, v30, v31
	v_lshlrev_b32_e32 v90, 2, v1
	v_lshrrev_b32_e32 v85, 2, v0
	v_cndmask_b32_e32 v43, v30, v36, vcc
	v_add_u32_e32 v30, -8, v36
	v_cmp_lt_i32_e32 vcc, v30, v31
	v_and_b32_e32 v85, 0x78, v85
	v_lshlrev_b32_e32 v146, 4, v0
	v_cndmask_b32_e32 v44, v30, v36, vcc
	v_add_u32_e32 v30, -16, v36
	v_cmp_lt_i32_e32 vcc, v30, v31
	v_lshlrev_b32_e32 v158, 2, v37
	v_mov_b32_e32 v37, 0x80
	v_cndmask_b32_e32 v45, v30, v36, vcc
	v_subrev_u32_e32 v30, 32, v36
	v_cmp_lt_i32_e32 vcc, v30, v31
	v_mov_b32_e32 v31, 0xfffffb80
	v_mov_b32_e32 v89, s3
	v_cndmask_b32_e32 v46, v30, v36, vcc
	v_and_b32_e32 v30, 63, v36
	v_cmp_ne_u32_e32 vcc, 63, v30
	v_lshl_or_b32 v173, v36, 2, v37
	v_mov_b32_e32 v37, 0x2000
	v_addc_co_u32_e32 v47, vcc, 0, v36, vcc
	v_cmp_gt_u32_e32 vcc, 62, v30
	v_lshlrev_b32_e32 v163, 2, v42
	v_lshlrev_b32_e32 v166, 2, v45
	v_cndmask_b32_e64 v48, 0, 2, vcc
	v_cmp_gt_u32_e32 vcc, 60, v30
	v_add_lshl_u32 v169, v48, v36, 2
	v_bfe_u32 v45, v0, 4, 1
	v_cndmask_b32_e64 v49, 0, 4, vcc
	v_cmp_gt_u32_e32 vcc, 56, v30
	v_add_lshl_u32 v170, v49, v36, 2
	v_lshlrev_b32_e32 v165, 2, v44
	v_cndmask_b32_e64 v50, 0, 8, vcc
	v_cmp_gt_u32_e32 vcc, 48, v30
	v_mov_b32_e32 v30, 0xba00
	v_add_lshl_u32 v171, v50, v36, 2
	v_cndmask_b32_e64 v51, 0, 16, vcc
	v_cmp_lt_u32_e32 vcc, s0, v0
	s_movk_i32 s0, 0x7f
	v_add_lshl_u32 v172, v51, v36, 2
	v_cndmask_b32_e32 v52, 0, v30, vcc
	v_cndmask_b32_e32 v53, 0, v31, vcc
	v_cmp_lt_u32_e32 vcc, s0, v0
	s_cselect_b64 s[0:1], -1, 0
	v_writelane_b32 v250, s0, 10
	v_cndmask_b32_e32 v54, 0, v30, vcc
	v_and_b32_e32 v30, 15, v0
	v_writelane_b32 v250, s1, 11
	s_add_u32 s0, s74, 0xb4000
	s_addc_u32 s1, s75, 0
	v_writelane_b32 v250, s0, 12
	s_bfe_u32 s33, s38, 0x20006
	s_lshl_b32 s41, s33, 4
	v_writelane_b32 v250, s1, 13
	s_lshr_b32 s0, s38, 8
	s_mul_i32 s1, s0, 0xba00
	s_add_i32 s39, s1, 0
	s_add_i32 s40, s39, 0x8c00
	s_mul_i32 s1, s33, 0x500
	s_mul_i32 s0, s0, 0xffff4700
	s_add_i32 s42, s39, s0
	s_add_i32 s47, s40, s1
	s_cmpk_gt_u32 s38, 0xff
	s_cselect_b64 s[0:1], -1, 0
	v_or_b32_e32 v32, s41, v58
	v_writelane_b32 v250, s0, 14
	s_cmpk_lt_u32 s38, 0x100
	v_cmp_gt_u32_e64 s[4:5], v30, v32
	v_writelane_b32 v250, s1, 15
	s_cselect_b64 s[0:1], -1, 0
	s_xor_b64 s[6:7], s[0:1], s[4:5]
	v_writelane_b32 v250, s6, 16
	v_or_b32_e32 v59, 1, v32
	v_or_b32_e32 v68, 2, v32
	v_writelane_b32 v250, s7, 17
	v_cmp_gt_u32_e64 s[6:7], v30, v59
	s_xor_b64 s[8:9], s[0:1], s[6:7]
	v_writelane_b32 v250, s8, 18
	v_or_b32_e32 v69, 3, v32
	v_or_b32_e32 v35, 16, v30
	v_writelane_b32 v250, s9, 19
	v_cmp_gt_u32_e64 s[8:9], v30, v68
	s_xor_b64 s[10:11], s[0:1], s[8:9]
	v_writelane_b32 v250, s10, 20
	v_cndmask_b32_e32 v55, 0, v31, vcc
	s_lshl_b32 s2, s33, 5
	v_writelane_b32 v250, s11, 21
	v_cmp_gt_u32_e64 s[10:11], v30, v69
	s_xor_b64 s[12:13], s[0:1], s[10:11]
	v_writelane_b32 v250, s12, 22
	v_cmp_eq_u32_e32 vcc, 1, v1
	s_add_i32 s43, s39, s2
	v_writelane_b32 v250, s13, 23
	v_cmp_gt_u32_e64 s[12:13], v35, v32
	s_xor_b64 s[14:15], s[0:1], s[12:13]
	v_writelane_b32 v250, s14, 24
	s_add_i32 s44, 0, 0x21a00
	v_cndmask_b32_e64 v71, 0, 1.0, vcc
	v_writelane_b32 v250, s15, 25
	v_cmp_gt_u32_e64 s[14:15], v35, v59
	s_xor_b64 s[16:17], s[0:1], s[14:15]
	v_writelane_b32 v250, s16, 26
	v_cmp_eq_u32_e32 vcc, 2, v1
	v_or_b32_e32 v34, 32, v30
	v_writelane_b32 v250, s17, 27
	v_cmp_gt_u32_e64 s[16:17], v35, v68
	s_xor_b64 s[18:19], s[0:1], s[16:17]
	v_writelane_b32 v250, s18, 28
	v_cndmask_b32_e64 v70, 0, 1.0, vcc
	v_cmp_eq_u32_e32 vcc, 3, v1
	v_writelane_b32 v250, s19, 29
	v_cmp_gt_u32_e64 s[18:19], v35, v69
	s_xor_b64 s[20:21], s[0:1], s[18:19]
	v_writelane_b32 v250, s20, 30
	s_cmp_eq_u32 s33, 1
	v_cndmask_b32_e64 v87, 0, 1.0, vcc
	v_writelane_b32 v250, s21, 31
	s_cselect_b64 s[20:21], -1, 0
	v_cmp_eq_u32_e32 vcc, 4, v1
	v_writelane_b32 v250, s20, 32
	v_cmp_gt_u32_e64 s[26:27], v34, v69
	v_cndmask_b32_e64 v73, 0, 1.0, vcc
	v_cmp_eq_u32_e32 vcc, 5, v1
	v_writelane_b32 v250, s21, 33
	v_cmp_gt_u32_e64 s[20:21], v34, v32
	v_cndmask_b32_e64 v72, 0, 1.0, vcc
	v_cmp_eq_u32_e32 vcc, 6, v1
	s_xor_b64 s[22:23], s[0:1], s[20:21]
	v_writelane_b32 v250, s22, 34
	v_cndmask_b32_e64 v113, 0, 1.0, vcc
	v_cmp_eq_u32_e32 vcc, 7, v1
	v_writelane_b32 v250, s23, 35
	v_cmp_gt_u32_e64 s[22:23], v34, v59
	v_cndmask_b32_e64 v117, 0, 1.0, vcc
	v_cmp_eq_u32_e32 vcc, 8, v1
	s_xor_b64 s[24:25], s[0:1], s[22:23]
	v_writelane_b32 v250, s24, 36
	v_cndmask_b32_e64 v75, 0, 1.0, vcc
	v_cmp_eq_u32_e32 vcc, 9, v1
	v_writelane_b32 v250, s25, 37
	v_cmp_gt_u32_e64 s[24:25], v34, v68
	v_cndmask_b32_e64 v74, 0, 1.0, vcc
	v_cmp_eq_u32_e32 vcc, 10, v1
	v_or_b32_e32 v33, 48, v30
	s_xor_b64 s[56:57], s[0:1], s[24:25]
	v_cndmask_b32_e64 v144, 0, 1.0, vcc
	v_cmp_eq_u32_e32 vcc, 11, v1
	s_xor_b64 s[58:59], s[0:1], s[26:27]
	s_cmp_eq_u32 s33, 2
	v_cndmask_b32_e64 v145, 0, 1.0, vcc
	v_cmp_eq_u32_e32 vcc, 12, v1
	v_cmp_gt_u32_e64 s[28:29], v33, v32
	v_cmp_gt_u32_e64 s[30:31], v33, v59
	v_cndmask_b32_e64 v77, 0, 1.0, vcc
	v_cmp_eq_u32_e32 vcc, 13, v1
	v_cmp_gt_u32_e64 s[34:35], v33, v68
	v_cmp_gt_u32_e64 s[36:37], v33, v69
	v_cndmask_b32_e64 v79, 0, 1.0, vcc
	v_cmp_eq_u32_e32 vcc, 14, v1
	v_lshrrev_b32_e32 v31, 3, v0
	s_cselect_b64 s[60:61], -1, 0
	s_xor_b64 s[62:63], s[0:1], s[28:29]
	s_xor_b64 s[64:65], s[0:1], s[30:31]
	s_xor_b64 s[90:91], s[0:1], s[34:35]
	v_cndmask_b32_e64 v78, 0, 1.0, vcc
	v_cmp_eq_u32_e32 vcc, 15, v1
	s_xor_b64 s[94:95], s[0:1], s[36:37]
	s_mul_i32 s45, s33, 0x300
	v_cndmask_b32_e64 v76, 0, 1.0, vcc
	v_cmp_gt_u32_e32 vcc, v57, v31
	s_cmp_eq_u32 s33, 3
	s_cselect_b64 s[96:97], -1, 0
	v_cndmask_b32_e64 v60, v66, 0, vcc
	v_cmp_lt_u32_e32 vcc, v57, v31
	s_add_i32 s45, s40, s45
	s_add_u32 s84, s74, 0x39c4000
	v_cndmask_b32_e32 v61, 0, v67, vcc
	v_cmp_gt_u32_e32 vcc, v63, v31
	s_addc_u32 s85, s75, 0
	s_bfe_u32 s46, s38, 0x10006
	v_cndmask_b32_e64 v62, v66, 0, vcc
	v_cmp_lt_u32_e32 vcc, v63, v31
	v_readlane_b32 s54, v250, 6
	s_bitcmp1_b32 s38, 6
	v_cndmask_b32_e32 v63, 0, v67, vcc
	v_cmp_gt_u32_e32 vcc, v65, v31
	v_readlane_b32 s55, v250, 7
	s_cselect_b64 s[86:87], -1, 0
	v_cndmask_b32_e64 v64, v66, 0, vcc
	v_cmp_lt_u32_e32 vcc, v65, v31
	s_ashr_i32 s55, s54, 31
	s_lshl_b64 s[0:1], s[54:55], 10
	v_cndmask_b32_e32 v65, 0, v67, vcc
	v_cmp_gt_u32_e32 vcc, v80, v31
	v_mov_b32_e32 v81, s1
	v_lshlrev_b32_e32 v84, 10, v30
	v_cndmask_b32_e64 v66, v66, 0, vcc
	v_cmp_lt_u32_e32 vcc, v80, v31
	v_or_b32_e32 v80, s0, v90
	s_lshl_b64 s[0:1], s[54:55], 14
	v_or3_b32 v84, s0, v84, v85
	v_mov_b32_e32 v85, s1
	v_or_b32_e32 v82, s0, v146
	v_mov_b32_e32 v83, s1
	v_lshl_add_u64 v[84:85], s[72:73], 0, v[84:85]
	s_mov_b64 s[0:1], 0x2000200
	v_lshl_add_u64 v[84:85], v[84:85], 0, s[0:1]
	v_or_b32_e32 v92, s41, v30
	s_movk_i32 s0, 0x110
	v_lshlrev_b32_e32 v151, 7, v59
	v_lshlrev_b32_e32 v59, 6, v0
	v_mad_u32_u24 v88, v92, s0, 0
	v_and_b32_e32 v59, 0x400, v59
	s_movk_i32 s0, 0x78
	v_and_or_b32 v154, v86, s0, v59
	v_mov_b32_e32 v86, s40
	s_movk_i32 s0, 0x50
	v_writelane_b32 v250, s47, 38
	v_mov_b32_e32 v59, s47
	v_lshl_or_b32 v98, s46, 4, v30
	v_mad_u32_u24 v59, v30, s0, v59
	v_mad_u32_u24 v157, v98, s0, v86
	v_readlane_b32 s0, v250, 9
	s_lshl_b32 s0, s0, 3
	s_and_b32 s0, s0, 16
	v_or_b32_e32 v99, s0, v58
	s_or_b32 s0, s0, 32
	v_or_b32_e32 v100, s0, v30
	v_or_b32_e32 v58, s0, v58
	v_sub_co_u32_e64 v101, s[0:1], s33, 1
	v_lshlrev_b32_e32 v102, 5, v101
	s_lshl_b32 s3, s46, 5
	v_add_u32_e32 v36, v0, v53
	v_lshlrev_b32_e32 v91, 1, v30
	v_mov_b32_e32 v97, s39
	v_add_u32_e32 v103, s39, v102
	s_add_i32 s39, s39, s3
	v_lshl_add_u32 v42, v36, 4, v37
	v_add_u32_e32 v36, v55, v0
	v_mov_b32_e32 v37, 0x4000
	v_lshl_add_u32 v44, v36, 4, v37
	v_lshlrev_b32_e32 v86, 3, v30
	v_add_u32_e32 v37, s39, v91
	v_cmp_eq_u32_e64 s[38:39], 0, v45
	v_lshlrev_b32_e32 v150, 7, v32
	v_lshlrev_b32_e32 v152, 7, v68
	v_lshlrev_b32_e32 v153, 7, v69
	v_lshl_or_b32 v174, v45, 10, v86
	v_cndmask_b32_e64 v45, 0, v89, s[38:39]
	v_lshl_add_u32 v147, v30, 2, s42
	v_add_u32_e32 v68, s44, v150
	v_add_u32_e32 v69, s44, v151
	v_add_u32_e32 v93, s44, v152
	v_add_u32_e32 v94, s44, v153
	v_mad_u32_u24 v156, v30, 48, s45
	v_lshlrev_b32_e32 v159, 2, v38
	s_add_i32 s3, 0, 0x1b200
	v_lshl_or_b32 v38, v101, 4, v30
	v_lshl_add_u32 v45, v30, 4, v45
	v_mul_u32_u24_e32 v48, 0x110, v30
	v_mul_u32_u24_e32 v50, 0x90, v30
	v_lshlrev_b32_e32 v30, 1, v35
	v_add_u32_e32 v96, s41, v1
	v_lshlrev_b32_e32 v160, 2, v39
	v_mov_b32_e32 v39, s3
	s_movk_i32 s3, 0x90
	v_add_u32_e32 v186, v68, v30
	v_add_u32_e32 v187, v69, v30
	v_add_u32_e32 v188, v93, v30
	v_add_u32_e32 v189, v94, v30
	v_lshlrev_b32_e32 v30, 1, v34
	v_lshlrev_b32_e32 v168, 2, v47
	v_mad_u32_u24 v47, v96, s3, v97
	v_mad_u32_u24 v175, v92, s3, v97
	v_mad_i32_i24 v176, v38, s3, v97
	v_add_u32_e32 v190, v68, v30
	v_add_u32_e32 v191, v69, v30
	v_add_u32_e32 v192, v93, v30
	v_add_u32_e32 v193, v94, v30
	v_lshlrev_b32_e32 v30, 1, v33
	v_lshlrev_b32_e32 v161, 2, v40
	v_mad_u32_u24 v40, v100, s3, v97
	v_mad_u32_u24 v177, v98, s3, v97
	v_mad_u32_u24 v38, v31, s3, 0
	v_mad_u32_u24 v39, v31, s3, v39
	v_add_u32_e32 v194, v68, v30
	v_add_u32_e32 v195, v69, v30
	v_add_u32_e32 v196, v93, v30
	v_add_u32_e32 v197, v94, v30
	v_add_u32_e32 v30, s2, v175
	v_add_u32_e32 v33, s2, v176
	v_add_u32_e32 v198, s2, v47
	v_cmp_eq_u32_e64 s[2:3], 0, v1
	v_lshl_add_u32 v95, v1, 1, s43
	s_mulk_i32 s33, 0x900
	v_writelane_b32 v250, s2, 39
	v_add_u32_e32 v184, 0, v90
	v_lshlrev_b32_e32 v155, 3, v56
	v_writelane_b32 v250, s3, 40
	v_cndmask_b32_e64 v90, 0, 1.0, s[2:3]
	s_add_i32 s2, s54, s70
	v_add_u32_e32 v178, s33, v95
	s_lshl_b32 s33, s2, 7
	s_movk_i32 s2, 0x300
	v_lshl_add_u32 v148, v32, 2, s42
	v_add_u32_e32 v56, s43, v155
	v_cmp_gt_u32_e64 s[42:43], s2, v0
	s_movk_i32 s2, 0x100
	v_add_u32_e32 v149, s44, v91
	v_cmp_gt_u32_e64 s[44:45], s2, v0
	s_mov_b32 s2, s54
	v_writelane_b32 v250, s2, 6
	v_or_b32_e32 v183, 3, v31
	s_mov_b32 s81, 0
	v_writelane_b32 v250, s3, 7
	v_cmp_gt_u32_e64 s[2:3], 2, v1
	v_lshlrev_b32_e32 v167, 2, v46
	v_mov_b32_e32 v46, 0x3db504f3
	v_writelane_b32 v250, s2, 41
	v_and_b32_e32 v180, 60, v31
	v_mul_u32_u24_e32 v31, 0x110, v183
	v_writelane_b32 v250, s3, 42
	v_cmp_gt_u32_e64 s[2:3], 4, v1
	v_and_b32_e32 v185, 48, v0
	s_mov_b32 s82, s81
	v_writelane_b32 v250, s2, 43
	s_mov_b32 s83, s81
	v_cndmask_b32_e32 v67, 0, v67, vcc
	v_writelane_b32 v250, s3, 44
	v_cmp_gt_u32_e64 s[2:3], 8, v1
	v_lshlrev_b32_e32 v162, 2, v41
	v_lshlrev_b32_e32 v164, 2, v43
	v_writelane_b32 v250, s2, 45
	v_add_u32_e32 v41, 0, v52
	v_add_u32_e32 v43, 0, v54
	v_writelane_b32 v250, s3, 46
	v_cmp_eq_u32_e64 s[2:3], 63, v1
	v_and_b32_e32 v36, 16, v0
	v_cndmask_b32_e64 v179, 1.0, v46, s[38:39]
	v_writelane_b32 v250, s2, 47
	v_mov_b32_e32 v89, 0
	v_mul_u32_u24_e32 v46, 0x110, v180
	v_writelane_b32 v250, s3, 48
	v_cmp_gt_u32_e64 s[2:3], 62, v1
	v_add_u32_e32 v49, 0, v185
	v_add_u32_e32 v34, v103, v91
	v_writelane_b32 v250, s2, 49
	v_mul_u32_u24_e32 v32, 0x90, v32
	v_lshlrev_b32_e32 v35, 1, v99
	v_writelane_b32 v250, s3, 50
	v_cmp_gt_u32_e64 s[2:3], 60, v1
	v_mul_u32_u24_e32 v47, 0x90, v58
	v_lshlrev_b32_e32 v51, 1, v58
	v_writelane_b32 v250, s2, 51
	v_lshlrev_b32_e32 v52, 1, v57
	s_ashr_i32 s71, s70, 31
	v_writelane_b32 v250, s3, 52
	v_cmp_gt_u32_e64 s[2:3], 56, v1
	s_mov_b32 s80, s81
	v_mov_b64_e32 v[236:237], s[82:83]
	v_writelane_b32 v250, s2, 53
	v_add_u32_e32 v211, v45, v31
	v_or_b32_e32 v181, 1, v180
	v_writelane_b32 v250, s3, 54
	v_cmp_gt_u32_e64 s[2:3], 48, v1
	v_or_b32_e32 v182, 2, v180
	v_cvt_pk_bf16_f32 v199, v90, s0
	v_add_u32_e32 v200, v102, v185
	v_or_b32_e32 v201, v60, v61
	v_bitop3_b32 v202, v60, v61, v60 bitop3:3
	v_or_b32_e32 v203, v62, v63
	v_bitop3_b32 v204, v62, v63, v62 bitop3:3
	v_or_b32_e32 v205, v64, v65
	v_bitop3_b32 v206, v64, v65, v64 bitop3:3
	v_or_b32_e32 v207, v66, v67
	v_bitop3_b32 v208, v66, v67, v66 bitop3:3
	v_mov_b32_e32 v92, v90
	v_mov_b32_e32 v93, v90
	v_mov_b64_e32 v[234:235], s[80:81]
	v_add_u32_e32 v209, v41, v42
	v_add_u32_e32 v210, v43, v44
	v_mov_b32_e32 v212, 0x3ecc95a3
	v_add_u32_e32 v213, v88, v185
	v_add_u32_e32 v214, v49, v48
	v_add_u32_e32 v215, v30, v185
	v_add_u32_e32 v216, v34, v32
	v_add_u32_e32 v217, v33, v155
	v_add_u32_e32 v218, v40, v185
	v_add_u32_e32 v219, v157, v35
	v_add_u32_e32 v220, v37, v47
	v_add_u32_e32 v221, v177, v51
	v_add_u32_e32 v222, v38, v52
	v_add_u32_e32 v223, v39, v52
	v_mov_b32_e32 v30, v89
	v_mov_b32_e32 v31, v89
	v_mov_b32_e32 v32, v89
	v_mov_b32_e32 v33, v89
	v_add_u32_e32 v224, v45, v46
	v_mov_b32_e32 v94, 0x3f317218
	v_mov_b32_e32 v225, 0x7f800000
	v_mov_b32_e32 v226, 0x7fc00000
	v_mov_b32_e32 v227, 0xff800000
	v_add_u32_e32 v228, v56, v50
	v_add_u32_e32 v229, v59, v185
	s_lshl_b32 s40, s70, 7
	s_lshl_b32 s41, s54, 3
	s_lshl_b32 s48, s70, 3
	s_add_i32 s49, 0, 0x18e00
	s_movk_i32 s50, 0x3000
	s_mov_b32 s51, 0xbfb8aa3b
	s_mov_b32 s52, 0x800000
	s_mov_b32 s53, s54
	v_cmp_ne_u32_e64 s[46:47], 0, v36
	v_cmp_gt_u32_e64 s[54:55], 16, v1
	v_writelane_b32 v250, s2, 55
	v_cmp_gt_u32_e64 s[66:67], 32, v1
	s_lshl_b64 s[82:83], s[70:71], 10
	s_lshl_b64 s[92:93], s[70:71], 14
	v_writelane_b32 v250, s3, 56
	v_readfirstlane_b32 s2, v0
	s_cmp_gt_u32 s2, 63
	s_cbranch_scc1 .Lp3pre_now
	s_and_b32 s68, s53, 7
	s_lshl_b32 s69, s68, 7
	v_or_b32_e32 v34, s69, v174
	v_lshlrev_b32_e32 v88, 2, v34
	v_lshl_add_u64 v[62:63], s[76:77], 0, v[88:89]
	v_add_co_u32_e32 v42, vcc, 0x3000, v62
	global_load_dwordx4 v[34:37], v88, s[76:77] offset:16
	global_load_dwordx4 v[38:41], v88, s[76:77]
	v_addc_co_u32_e32 v43, vcc, 0, v63, vcc
	global_load_dwordx4 v[50:53], v[42:43], off
	v_add_co_u32_e32 v42, vcc, 0x6000, v62
	s_mov_b64 s[2:3], 0x6000
	s_nop 0
	v_addc_co_u32_e32 v43, vcc, 0, v63, vcc
	v_add_co_u32_e32 v46, vcc, 0x9000, v62
	global_load_dwordx4 v[54:57], v[42:43], off
	s_nop 0
	v_addc_co_u32_e32 v47, vcc, 0, v63, vcc
	global_load_dwordx4 v[58:61], v[46:47], off
	v_lshl_add_u64 v[42:43], v[62:63], 0, s[2:3]
	s_mov_b64 s[2:3], 0x9000
	v_lshl_add_u64 v[46:47], v[62:63], 0, s[2:3]
	global_load_dwordx4 v[42:45], v[42:43], off offset:16
	s_mov_b64 s[2:3], 0x3000
	global_load_dwordx4 v[46:49], v[46:47], off offset:16
	v_lshl_add_u64 v[62:63], v[62:63], 0, s[2:3]
	global_load_dwordx4 v[62:65], v[62:63], off offset:16
	v_and_b32_e32 v66, 31, v0
	v_lshlrev_b32_e32 v66, 4, v66
	v_add_u32_e32 v66, 0x26a00, v66
	v_cmp_gt_u32_e32 vcc, 32, v0
	s_and_saveexec_b64 s[2:3], vcc
	s_waitcnt vmcnt(0)
	ds_write_b128 v66, v[34:37]
	ds_write_b128 v66, v[38:41] offset:512
	ds_write_b128 v66, v[50:53] offset:1024
	ds_write_b128 v66, v[54:57] offset:1536
	ds_write_b128 v66, v[58:61] offset:2048
	ds_write_b128 v66, v[42:45] offset:2560
	ds_write_b128 v66, v[46:49] offset:3072
	ds_write_b128 v66, v[62:65] offset:3584
	s_or_b64 exec, exec, s[2:3]
.Lp3pre_now:
	v_readfirstlane_b32 s2, v0
	s_lshr_b32 s2, s2, 6
	s_mul_i32 s3, s2, s48
	s_add_i32 s3, s3, s41
	s_and_b32 s71, s3, 0xffffffc0
	s_and_b32 s68, s53, 7
	s_mul_i32 s88, s2, s82
	s_mov_b32 s89, 0
	s_lshl_b32 s3, s2, 10
	s_add_i32 s3, s3, 0x1c200
	v_lshl_add_u64 v[56:57], v[80:81], 0, s[88:89]
	v_add_u32_e32 v58, s3, v184
	v_or_b32_e32 v34, s71, v1
	v_ashrrev_i32_e32 v35, 31, v34
	v_readlane_b32 s2, v250, 12
	v_lshlrev_b64 v[34:35], 7, v[34:35]
	v_readlane_b32 s3, v250, 13
	s_lshl_b32 s80, s68, 2
	v_mov_b32_e32 v38, s80
	v_lshl_add_u64 v[34:35], s[2:3], 0, v[34:35]
	v_readlane_b32 s2, v250, 4
	v_readlane_b32 s3, v250, 5
	v_lshl_add_u64 v[34:35], v[34:35], 0, s[80:81]
	s_nop 3
	global_load_dword v39, v38, s[2:3]
	global_load_dword v37, v[34:35], off
	global_load_dword v40, v[34:35], off offset:64
	global_load_dword v36, v[34:35], off offset:32
	s_nop 0
	global_load_dword v38, v38, s[78:79]
	s_add_u32 s68, s78, s80
	s_addc_u32 s69, s79, 0
	s_add_u32 s88, s2, s80
	s_mov_b32 s2, 0x41a00000
	s_addc_u32 s89, s3, 0
	s_waitcnt vmcnt(2)
	v_add_f32_e32 v39, v40, v39
	v_cmp_nlt_f32_e32 vcc, s2, v39
	s_and_saveexec_b64 s[2:3], vcc
	s_cbranch_execz .Lp3pre_330
	v_mul_f32_e32 v39, 0x3fb8aa3b, v39
	v_exp_f32_e32 v39, v39
	s_mov_b32 s71, 0x3f2aaaab
	v_add_f32_e32 v42, 1.0, v39
	v_frexp_mant_f32_e32 v44, v42
	v_cvt_f64_f32_e32 v[40:41], v42
	v_frexp_exp_i32_f64_e32 v40, v[40:41]
	v_cmp_gt_f32_e32 vcc, s71, v44
	v_add_f32_e32 v43, -1.0, v42
	v_sub_f32_e32 v45, v43, v42
	v_subbrev_co_u32_e32 v48, vcc, 0, v40, vcc
	v_sub_u32_e32 v40, 0, v48
	v_sub_f32_e32 v43, v39, v43
	v_add_f32_e32 v45, 1.0, v45
	v_ldexp_f32 v41, v42, v40
	v_add_f32_e32 v43, v43, v45
	v_add_f32_e32 v42, -1.0, v41
	v_add_f32_e32 v44, 1.0, v41
	v_ldexp_f32 v40, v43, v40
	v_add_f32_e32 v43, 1.0, v42
	v_add_f32_e32 v45, -1.0, v44
	v_sub_f32_e32 v43, v41, v43
	v_sub_f32_e32 v41, v41, v45
	v_add_f32_e32 v43, v40, v43
	v_add_f32_e32 v40, v40, v41
	v_add_f32_e32 v49, v44, v40
	v_rcp_f32_e32 v51, v49
	v_sub_f32_e32 v41, v49, v44
	v_sub_f32_e32 v50, v40, v41
	v_add_f32_e32 v41, v42, v43
	v_mul_f32_e32 v53, v41, v51
	v_sub_f32_e32 v40, v41, v42
	v_mul_f32_e32 v42, v49, v53
	v_fma_f32 v44, v53, v49, -v42
	v_fmac_f32_e32 v44, v53, v50
	v_sub_f32_e32 v52, v43, v40
	v_add_f32_e32 v40, v42, v44
	v_sub_f32_e32 v43, v41, v40
	v_pk_add_f32 v[46:47], v[40:41], v[42:43] neg_lo:[0,1] neg_hi:[0,1]
	v_mov_b32_e32 v45, v40
	v_pk_add_f32 v[40:41], v[46:47], v[44:45] neg_lo:[0,1] neg_hi:[0,1]
	s_mov_b32 s71, 0x3f317218
	v_add_f32_e32 v41, v52, v41
	v_add_f32_e32 v40, v40, v41
	v_add_f32_e32 v41, v43, v40
	v_mul_f32_e32 v52, v51, v41
	v_mul_f32_e32 v42, v49, v52
	v_fma_f32 v44, v52, v49, -v42
	v_fmac_f32_e32 v44, v52, v50
	v_sub_f32_e32 v43, v43, v41
	v_add_f32_e32 v49, v40, v43
	v_add_f32_e32 v40, v42, v44
	v_sub_f32_e32 v43, v41, v40
	v_pk_add_f32 v[46:47], v[40:41], v[42:43] neg_lo:[0,1] neg_hi:[0,1]
	v_mov_b32_e32 v45, v40
	v_pk_add_f32 v[40:41], v[46:47], v[44:45] neg_lo:[0,1] neg_hi:[0,1]
	s_nop 0
	v_add_f32_e32 v41, v49, v41
	v_add_f32_e32 v40, v40, v41
	v_add_f32_e32 v41, v53, v52
	v_add_f32_e32 v40, v43, v40
	v_sub_f32_e32 v42, v41, v53
	v_mul_f32_e32 v40, v51, v40
	v_sub_f32_e32 v42, v52, v42
	v_add_f32_e32 v42, v42, v40
	v_add_f32_e32 v44, v41, v42
	v_mul_f32_e32 v45, v44, v44
	v_fmamk_f32 v40, v45, 0x3e9b6dac, v212
	v_fmaak_f32 v95, v45, v40, 0x3f2aaada
	v_cvt_f32_i32_e32 v40, v48
	v_sub_f32_e32 v41, v44, v41
	v_sub_f32_e32 v41, v42, v41
	v_ldexp_f32 v46, v41, 1
	v_mul_f32_e32 v41, v44, v45
	v_ldexp_f32 v43, v44, 1
	v_pk_mul_f32 v[44:45], v[40:41], v[94:95]
	s_nop 0
	v_fma_f32 v42, v40, s71, -v44
	v_fmac_f32_e32 v42, 0xb102e308, v40
	v_pk_add_f32 v[40:41], v[44:45], v[42:43]
	s_mov_b32 s71, 0x7f800000
	v_sub_f32_e32 v43, v41, v43
	v_sub_f32_e32 v43, v45, v43
	v_add_f32_e32 v47, v46, v43
	v_mov_b32_e32 v46, v44
	v_pk_add_f32 v[44:45], v[40:41], v[44:45] neg_lo:[0,1] neg_hi:[0,1]
	v_pk_add_f32 v[48:49], v[40:41], v[46:47]
	v_mov_b32_e32 v43, v40
	v_mov_b32_e32 v45, v49
	v_pk_add_f32 v[50:51], v[42:43], v[44:45] neg_lo:[0,1] neg_hi:[0,1]
	v_pk_add_f32 v[42:43], v[42:43], v[44:45]
	v_mov_b32_e32 v46, v47
	v_pk_add_f32 v[44:45], v[42:43], v[40:41] op_sel:[1,0] op_sel_hi:[0,1] neg_lo:[0,1] neg_hi:[0,1]
	v_pk_add_f32 v[52:53], v[48:49], v[44:45] op_sel_hi:[1,0] neg_lo:[0,1] neg_hi:[0,1]
	v_mov_b32_e32 v48, v49
	v_mov_b32_e32 v49, v43
	v_pk_mov_b32 v[44:45], v[40:41], v[44:45] op_sel:[1,0]
	v_mov_b32_e32 v47, v40
	v_pk_add_f32 v[44:45], v[48:49], v[44:45] neg_lo:[0,1] neg_hi:[0,1]
	v_mov_b32_e32 v52, v50
	v_pk_add_f32 v[40:41], v[46:47], v[44:45] neg_lo:[0,1] neg_hi:[0,1]
	v_mov_b32_e32 v51, v43
	v_pk_add_f32 v[44:45], v[52:53], v[40:41]
	v_cmp_neq_f32_e32 vcc, s71, v39
	v_pk_add_f32 v[46:47], v[44:45], v[44:45] op_sel:[0,1] op_sel_hi:[1,0]
	s_mov_b32 s71, 0x33800000
	v_pk_add_f32 v[42:43], v[42:43], v[46:47] op_sel:[1,0] op_sel_hi:[0,1]
	v_mov_b32_e32 v45, v42
	v_pk_add_f32 v[48:49], v[44:45], v[50:51] neg_lo:[0,1] neg_hi:[0,1]
	v_mov_b32_e32 v41, v46
	v_sub_f32_e32 v43, v44, v48
	v_pk_add_f32 v[40:41], v[40:41], v[48:49] neg_lo:[0,1] neg_hi:[0,1]
	v_sub_f32_e32 v43, v50, v43
	v_add_f32_e32 v40, v40, v43
	v_add_f32_e32 v40, v40, v41
	v_add_f32_e32 v40, v42, v40
	v_cndmask_b32_e32 v40, v225, v40, vcc
	v_cmp_ngt_f32_e32 vcc, -1.0, v39
	s_nop 1
	v_cndmask_b32_e32 v40, v226, v40, vcc
	v_cmp_neq_f32_e32 vcc, -1.0, v39
	s_nop 1
	v_cndmask_b32_e32 v40, v227, v40, vcc
	v_cmp_lt_f32_e64 vcc, |v39|, s71
	s_nop 1
	v_cndmask_b32_e32 v39, v40, v39, vcc

.LBB0_313:
	v_add_u32_e32 v230, 0, v146
	v_add_u32_e32 v34, s49, v146
	ds_write_b128 v230, v[234:237] offset:54272
	ds_write_b128 v209, v[234:237] offset:54272
	ds_write_b128 v210, v[234:237] offset:54272
	s_and_saveexec_b64 s[2:3], s[42:43]
	ds_write_b128 v34, v[30:33] offset:6144
	s_or_b64 exec, exec, s[2:3]
	s_and_saveexec_b64 s[2:3], s[44:45]
	ds_write_b128 v34, v[30:33] offset:14336
	s_or_b64 exec, exec, s[2:3]
	s_and_b32 s68, s53, 7
	s_lshl_b32 s69, s68, 7
	v_and_b32_e32 v88, 31, v0
	v_lshlrev_b32_e32 v88, 4, v88
	v_add_u32_e32 v88, 0x26a00, v88
	ds_read_b128 v[34:37], v88
	ds_read_b128 v[38:41], v88 offset:512
	ds_read_b128 v[50:53], v88 offset:1024
	ds_read_b128 v[54:57], v88 offset:1536
	ds_read_b128 v[58:61], v88 offset:2048
	ds_read_b128 v[42:45], v88 offset:2560
	ds_read_b128 v[46:49], v88 offset:3072
	ds_read_b128 v[62:65], v88 offset:3584
	s_waitcnt vmcnt(0)
	v_lshlrev_b32_e32 v122, 16, v2
	v_and_b32_e32 v123, 0xffff0000, v2
	v_lshlrev_b32_e32 v66, 16, v6
	v_and_b32_e32 v68, 0xffff0000, v6
	v_mov_b32_e32 v67, v122
	v_mov_b32_e32 v69, v123
	v_lshlrev_b32_e32 v96, 16, v10
	v_and_b32_e32 v97, 0xffff0000, v10
	v_lshlrev_b32_e32 v104, 16, v14
	v_and_b32_e32 v105, 0xffff0000, v14
	v_mov_b32_e32 v124, v104
	v_mov_b32_e32 v125, v96
	v_mov_b32_e32 v126, v105
	v_mov_b32_e32 v127, v97
	v_lshlrev_b32_e32 v88, 16, v9
	v_lshlrev_b32_e32 v108, 16, v7
	v_and_b32_e32 v120, 0xffff0000, v7
	v_lshlrev_b32_e32 v109, 16, v3
	v_and_b32_e32 v121, 0xffff0000, v3
	v_lshlrev_b32_e32 v98, 16, v11
	v_and_b32_e32 v99, 0xffff0000, v11
	v_and_b32_e32 v107, 0xffff0000, v15
	v_lshlrev_b32_e32 v106, 16, v15
	v_lshlrev_b32_e32 v100, 16, v12
	v_lshlrev_b32_e32 v114, 16, v16
	v_mov_b32_e32 v128, v106
	v_mov_b32_e32 v129, v98
	v_mov_b32_e32 v130, v107
	v_mov_b32_e32 v131, v99
	v_and_b32_e32 v101, 0xffff0000, v12
	v_and_b32_e32 v115, 0xffff0000, v16
	v_lshlrev_b32_e32 v102, 16, v8
	v_and_b32_e32 v118, 0xffff0000, v8
	v_and_b32_e32 v110, 0xffff0000, v9
	v_and_b32_e32 v111, 0xffff0000, v5
	s_and_b32 s71, s41, 0xffffffc0
	s_waitcnt lgkmcnt(7)
	v_mul_f32_e32 v133, v36, v88
	s_waitcnt lgkmcnt(6)
	v_mov_b32_e32 v134, v38
	v_mov_b32_e32 v136, v39
	v_mov_b32_e32 v138, v40
	s_waitcnt lgkmcnt(5)
	v_mov_b32_e32 v135, v50
	v_mov_b32_e32 v137, v51
	v_pk_mul_f32 v[66:67], v[134:135], v[66:67]
	v_pk_mul_f32 v[68:69], v[136:137], v[68:69]
	v_mov_b32_e32 v248, v66
	v_mov_b32_e32 v249, v68
	v_pk_add_f32 v[248:249], v[248:249], 0 op_sel_hi:[1,0]
	v_mov_b32_e32 v68, v67
	s_waitcnt lgkmcnt(4)
	v_mov_b32_e32 v142, v54
	v_mov_b32_e32 v232, v55
	v_pk_add_f32 v[66:67], v[248:249], v[68:69]
	s_waitcnt lgkmcnt(3)
	v_mov_b32_e32 v143, v58
	v_mov_b32_e32 v233, v59
	v_pk_mul_f32 v[142:143], v[142:143], v[124:125]
	v_pk_mul_f32 v[232:233], v[232:233], v[126:127]
	v_mov_b32_e32 v68, v142
	v_mov_b32_e32 v69, v232
	v_pk_add_f32 v[66:67], v[66:67], v[68:69]
	v_mov_b32_e32 v232, v143
	v_pk_add_f32 v[66:67], v[66:67], v[232:233]
	v_mov_b32_e32 v140, v41
	v_mul_f32_e32 v68, 0xbfb8aa3b, v66
	v_exp_f32_e32 v68, v68
	v_mul_f32_e32 v69, 0xbfb8aa3b, v67
	v_exp_f32_e32 v88, v69
	v_mov_b32_e32 v139, v52
	v_add_f32_e32 v68, 1.0, v68
	v_rcp_f32_e32 v142, v68
	v_add_f32_e32 v68, 1.0, v88
	v_rcp_f32_e32 v143, v68
	v_mov_b32_e32 v141, v53
	v_pk_mul_f32 v[138:139], v[138:139], v[108:109]
	v_pk_mul_f32 v[140:141], v[140:141], v[120:121]
	v_mov_b32_e32 v134, v56
	v_mov_b32_e32 v136, v57
	v_mov_b32_e32 v135, v60
	v_mov_b32_e32 v137, v61
	v_pk_mul_f32 v[66:67], v[66:67], v[142:143]
	v_mov_b32_e32 v142, v140
	v_mov_b32_e32 v143, v138
	s_waitcnt lgkmcnt(2)
	v_mov_b32_e32 v238, v42
	v_pk_mul_f32 v[128:129], v[134:135], v[128:129]
	v_pk_mul_f32 v[130:131], v[136:137], v[130:131]
	s_waitcnt lgkmcnt(1)
	v_mov_b32_e32 v239, v46
	v_mov_b32_e32 v124, v114
	v_mov_b32_e32 v125, v100
	v_pk_add_f32 v[142:143], v[142:143], 0 op_sel_hi:[1,0]
	v_mov_b32_e32 v138, v141
	v_pk_mul_f32 v[134:135], v[238:239], v[124:125]
	v_mov_b32_e32 v124, v43
	v_mov_b32_e32 v125, v47
	v_mov_b32_e32 v126, v115
	v_mov_b32_e32 v127, v101
	v_pk_add_f32 v[138:139], v[142:143], v[138:139]
	v_mov_b32_e32 v140, v130
	v_mov_b32_e32 v141, v128
	v_pk_mul_f32 v[136:137], v[124:125], v[126:127]
	v_lshlrev_b32_e32 v124, 16, v4
	v_pk_add_f32 v[138:139], v[138:139], v[140:141]
	v_mov_b32_e32 v128, v131
	v_and_b32_e32 v125, 0xffff0000, v4
	v_mov_b32_e32 v126, v34
	s_waitcnt lgkmcnt(0)
	v_mov_b32_e32 v127, v62
	v_mov_b32_e32 v103, v124
	v_pk_add_f32 v[128:129], v[138:139], v[128:129]
	v_pk_mul_f32 v[238:239], v[126:127], v[102:103]
	v_mov_b32_e32 v102, v35
	v_mov_b32_e32 v103, v63
	v_mov_b32_e32 v119, v125
	v_mul_f32_e32 v68, 0xbfb8aa3b, v129
	v_pk_mul_f32 v[240:241], v[102:103], v[118:119]
	v_exp_f32_e32 v68, v68
	v_mul_f32_e32 v88, 0xbfb8aa3b, v128
	v_exp_f32_e32 v88, v88
	v_mov_b32_e32 v140, v240
	v_mov_b32_e32 v141, v238
	v_pk_add_f32 v[140:141], v[140:141], 0 op_sel_hi:[1,0]
	v_mov_b32_e32 v238, v241
	v_pk_add_f32 v[140:141], v[140:141], v[238:239]
	v_mov_b32_e32 v142, v136
	v_mov_b32_e32 v143, v134
	v_add_f32_e32 v68, 1.0, v68
	v_pk_add_f32 v[140:141], v[140:141], v[142:143]
	v_mov_b32_e32 v134, v137
	v_rcp_f32_e32 v139, v68
	v_add_f32_e32 v68, 1.0, v88
	v_pk_add_f32 v[134:135], v[140:141], v[134:135]
	v_rcp_f32_e32 v138, v68
	v_mul_f32_e32 v68, 0xbfb8aa3b, v135
	v_exp_f32_e32 v68, v68
	v_and_b32_e32 v103, 0xffff0000, v13
	v_and_b32_e32 v119, 0xffff0000, v17
	v_mov_b32_e32 v232, v37
	v_mov_b32_e32 v233, v65
	v_mov_b32_e32 v126, v45
	v_mov_b32_e32 v127, v49
	v_mov_b32_e32 v246, v119
	v_mov_b32_e32 v247, v103
	v_pk_mul_f32 v[232:233], v[232:233], v[110:111]
	v_pk_mul_f32 v[246:247], v[126:127], v[246:247]
	v_lshlrev_b32_e32 v126, 16, v5
	v_add_f32_e32 v68, 1.0, v68
	v_mov_b32_e32 v132, v232
	v_lshlrev_b32_e32 v118, 16, v17
	v_mul_f32_e32 v69, v64, v126
	v_rcp_f32_e32 v137, v68
	v_pk_add_f32 v[132:133], v[132:133], 0 op_sel_hi:[1,0]
	v_mov_b32_e32 v68, v233
	v_lshlrev_b32_e32 v102, 16, v13
	v_mul_f32_e32 v245, v44, v118
	v_pk_add_f32 v[68:69], v[132:133], v[68:69]
	v_mov_b32_e32 v244, v246
	v_mul_f32_e32 v243, v48, v102
	v_pk_add_f32 v[68:69], v[68:69], v[244:245]
	v_mov_b32_e32 v242, v247
	v_mul_f32_e32 v88, 0xbfb8aa3b, v134
	v_pk_add_f32 v[68:69], v[68:69], v[242:243]
	v_exp_f32_e32 v88, v88
	v_mul_f32_e32 v91, 0xbfb8aa3b, v69
	v_exp_f32_e32 v91, v91
	v_mul_f32_e32 v95, 0xbfb8aa3b, v68
	v_exp_f32_e32 v95, v95
	v_add_f32_e32 v88, 1.0, v88
	v_rcp_f32_e32 v136, v88
	v_add_f32_e32 v88, 1.0, v91
	v_rcp_f32_e32 v133, v88
	v_add_f32_e32 v88, 1.0, v95
	v_pk_mul_f32 v[130:131], v[66:67], v[66:67]
	v_pk_mul_f32 v[128:129], v[128:129], v[138:139]
	v_rcp_f32_e32 v132, v88
	v_pk_mul_f32 v[138:139], v[128:129], v[128:129]
	v_add_f32_e32 v88, v130, v131
	v_pk_mul_f32 v[134:135], v[134:135], v[136:137]
	v_add_f32_e32 v88, v139, v88
	v_pk_mul_f32 v[136:137], v[134:135], v[134:135]
	v_add_f32_e32 v88, v138, v88
	v_pk_mul_f32 v[68:69], v[68:69], v[132:133]
	v_add_f32_e32 v88, v137, v88
	v_pk_mul_f32 v[132:133], v[68:69], v[68:69]
	v_add_f32_e32 v88, v136, v88
	v_add_f32_e32 v88, v133, v88
	v_add_f32_e32 v88, v132, v88
	ds_bpermute_b32 v91, v158, v88
	s_waitcnt lgkmcnt(0)
	v_add_f32_e32 v88, v88, v91
	ds_bpermute_b32 v91, v159, v88
	s_waitcnt lgkmcnt(0)
	v_add_f32_e32 v88, v88, v91
	ds_bpermute_b32 v91, v160, v88
	s_waitcnt lgkmcnt(0)
	v_add_f32_e32 v88, v88, v91
	ds_bpermute_b32 v91, v161, v88
	s_waitcnt lgkmcnt(0)
	v_add_f32_e32 v88, v88, v91
	v_add_f32_e32 v88, 0x358637bd, v88
	v_mul_f32_e32 v91, 0x4b800000, v88
	v_cmp_gt_f32_e32 vcc, s52, v88
	s_nop 1
	v_cndmask_b32_e32 v88, v88, v91, vcc
	v_rsq_f32_e32 v88, v88
	s_nop 0
	v_mul_f32_e32 v91, 0x45800000, v88
	v_cndmask_b32_e32 v88, v88, v91, vcc
	v_mul_f32_e32 v88, v179, v88
	v_mul_f32_e32 v116, v66, v88
	v_mul_f32_e32 v232, v67, v88
	v_mul_f32_e32 v112, v129, v88
	v_mul_f32_e32 v231, v128, v88
	v_mul_f32_e32 v110, v135, v88
	v_mul_f32_e32 v95, v134, v88
	v_mul_f32_e32 v108, v69, v88
	v_mul_f32_e32 v91, v68, v88
	v_cvt_pk_bf16_f32 v66, v116, v232
	v_cvt_pk_bf16_f32 v67, v112, v231
	v_cvt_pk_bf16_f32 v68, v110, v95
	v_cvt_pk_bf16_f32 v69, v108, v91
	v_lshlrev_b32_e32 v88, 1, v86
	ds_write_b128 v224, v[66:69]
	s_and_saveexec_b64 s[2:3], s[38:39]
	s_cbranch_execz .LBB0_319
	v_add_u32_e32 v128, s71, v180
	v_ashrrev_i32_e32 v129, 31, v128
	v_lshlrev_b64 v[128:129], 11, v[128:129]
	v_lshl_add_u64 v[128:129], s[72:73], 0, v[128:129]
	s_lshl_b32 s80, s69, 1
	v_lshl_add_u64 v[128:129], v[128:129], 0, s[80:81]
	v_lshl_add_u64 v[128:129], v[128:129], 0, v[88:89]
	global_store_dwordx4 v[128:129], v[66:69], off
